# down-projection GEMM uses 288-row tiles (32 sample rows folded into each 256-row unit, extra MFMAs + LDS-DMA slot), DN small-tile GEMM removed
# speedup vs baseline: 1.0837x; 1.0234x over previous
; #define PG8_STAGE(bufoff, gbase, voff) do { _Pragma("unroll") for (int _i = 0; _i < 2; ++_i) \
;         __builtin_amdgcn_global_load_lds((const unsigned*)((const char*)(gbase) + (voff)[_i]), (PG8_LAS unsigned*)(lds + (bufoff) + ldsw + _i * 8192), 16, 0, 0); } while (0)
; #define PG8_WAIT_V(n) asm volatile("s_waitcnt vmcnt(" #n ")" ::: "memory")
; #define PG8_BAR __builtin_amdgcn_s_barrier()
; template <class Epi, class Sched, bool ALIGN_EPI = false, bool SP2 = false>
; __device__ __forceinline__ void gemm_phase(PG8_LAS unsigned char* lds, const Gemm g, const Sched& S, const Epi& E) {
;     ...
;     const int tid = tid_, wid = __builtin_amdgcn_readfirstlane(tid >> 6), lane = tid & 63, wr = wid >> 2, wc = wid & 3, fr = lane & 15, fq = lane >> 4;
;     const int K = g.K, nt = K / BK;
;     unsigned voffA[2], voffB[2];
; #pragma unroll
;     for (int i = 0; i < 2; ++i) { int R, C; stage_rc(tid * 16 + i * 8192, R, C); const int Rb = Epi::PERM ? ((R & ~31) + perm32(R & 31)) : R;
;         voffA[i] = (unsigned)(R * K + C) * 2u; voffB[i] = (unsigned)(Rb * K + C) * 2u; }
;     const size_t kstep = (size_t)(BK * 2);
;     const size_t hstep = (size_t)HALF * K * 2;
;     const size_t tstep = 2 * hstep;
;     const unsigned ldsw = (unsigned)wid * 1024u;
;     const int aoff = lds_byte(wr * 64 + fr, fq * 8), boff = lds_byte(wc * 32 + fr, fq * 8);
;     ...
;     Unit cur, nxt; int ui = 0;
;     if (!S.next(0, cur)) return;
;     f32x4 acc[2][2][4][2];
; #pragma unroll
;     for (int a = 0; a < 2; ++a)
; #pragma unroll
;         for (int b = 0; b < 2; ++b)
; #pragma unroll
;             for (int m = 0; m < 4; ++m)
; #pragma unroll
;                 for (int n = 0; n < 2; ++n) acc[a][b][m][n] = (f32x4){0.f, 0.f, 0.f, 0.f};
;     bf16x8 At[4][2], B0[2][2], B1[2][2];
;     const char* cA = (const char*)g.A + (size_t)cur.pm * tstep; const char* cB = (const char*)g.Bt + (size_t)cur.pn * tstep;
;     S.a_ready(cur);
;     if constexpr (SP2) {
;         PG8_STAGE(PG8_SB(0, 0), cB, voffB); PG8_STAGE(PG8_SB(0, 1), cB + hstep, voffB); PG8_STAGE(PG8_SA(0, 0), cA, voffA); PG8_STAGE(PG8_SA(0, 1), cA + hstep, voffA);
;         if (wr == 1) PG8_BAR;
;         PG8_WAIT_V(2); PG8_BAR;
;         PG8_STAGE(PG8_SB(1, 0), cB + kstep, voffB); PG8_STAGE(PG8_SA(1, 0), cA + kstep, voffA); PG8_STAGE(PG8_SB(1, 1), cB + hstep + kstep, voffB);
;         PG8_WAIT_V(6); PG8_BAR;
.LBB0_443:
	s_and_b64 vcc, exec, s[22:23]
	s_cbranch_vccz .LBB0_494
	v_readlane_b32 s0, v251, 17
	v_mov_b32_e32 v16, v216
	v_readlane_b32 s1, v251, 18
	s_andn2_b64 vcc, exec, s[0:1]
	v_readfirstlane_b32 s0, v16
	s_cbranch_vccnz .LBB0_493
	v_lshlrev_b32_e32 v0, 4, v16
	v_add_u32_e32 v1, 0x2000, v0
	v_ashrrev_i32_e32 v2, 31, v1
	v_lshrrev_b32_e32 v2, 22, v2
	v_add_u32_e32 v2, v1, v2
	v_ashrrev_i32_e32 v8, 10, v2
	v_mul_i32_i24_e32 v2, 0x400, v8
	v_sub_u32_e32 v1, v1, v2
	v_lshrrev_b32_e32 v2, 4, v1
	v_bitop3_b32 v1, v2, v1, 32 bitop3:0x6c
	v_ashrrev_i32_e32 v2, 31, v1
	v_lshrrev_b32_e32 v2, 26, v2
	v_add_u32_e32 v2, v1, v2
	v_lshlrev_b32_e32 v3, 3, v8
	s_add_u32 s8, s48, 0xbd00000
	v_readlane_b32 s2, v255, 19
	v_ashrrev_i32_e32 v9, 6, v2
	v_and_b32_e32 v3, -16, v3
	s_addc_u32 s9, s49, 0
	v_readlane_b32 s3, v255, 20
	s_mul_i32 s28, s2, 0x580000
	v_add_u32_e32 v3, v9, v3
	s_mul_hi_i32 s7, s2, 0x580000
	s_add_u32 s1, s48, s28
	v_and_b32_e32 v4, 3, v9
	s_mov_b32 s3, 0xffffe0
	v_lshrrev_b32_e32 v5, 2, v3
	v_lshlrev_b32_e32 v6, 1, v3
	v_and_b32_e32 v2, 0xc0, v2
	s_addc_u32 s2, s49, s7
	v_and_or_b32 v4, v3, s3, v4
	v_and_b32_e32 v5, 4, v5
	v_and_b32_e32 v6, 24, v6
	v_sub_u32_e32 v1, v1, v2
	s_add_u32 s10, s1, 0x4300000
	v_or3_b32 v4, v4, v5, v6
	v_lshlrev_b32_e32 v5, 5, v8
	v_ashrrev_i16_sdwa v1, v221, sext(v1) dst_sel:DWORD dst_unused:UNUSED_PAD src0_sel:DWORD src1_sel:BYTE_0
	s_addc_u32 s11, s2, 0
	v_and_b32_e32 v10, 32, v5
	v_bfe_i32 v11, v1, 0, 16
	s_movk_i32 s2, 0xb00
	v_mul_u32_u24_e32 v4, 0xb00, v4
	v_add_u32_e32 v1, v10, v11
	v_mul_lo_u32 v2, v3, s2
	v_add_lshl_u32 v194, v4, v1, 1
	v_add_lshl_u32 v196, v1, v2, 1
	v_bfe_i32 v1, v16, 27, 1
	v_lshrrev_b32_e32 v1, 22, v1
	v_add_u32_e32 v1, v0, v1
	v_and_b32_e32 v1, 0xfffffc00, v1
	v_sub_u32_e32 v0, v0, v1
	v_lshrrev_b32_e32 v1, 4, v0
	v_ashrrev_i32_e32 v2, 31, v16
	v_bitop3_b32 v0, v1, v0, 32 bitop3:0x6c
	v_lshrrev_b32_e32 v2, 26, v2
	v_ashrrev_i32_e32 v1, 31, v0
	v_add_u32_e32 v2, v16, v2
	v_lshrrev_b32_e32 v1, 26, v1
	v_ashrrev_i32_e32 v13, 6, v2
	v_add_u32_e32 v1, v0, v1
	v_lshlrev_b32_e32 v2, 3, v13
	v_ashrrev_i32_e32 v12, 6, v1
	v_and_b32_e32 v2, -16, v2
	v_add_u32_e32 v2, v12, v2
	v_and_b32_e32 v3, 3, v12
	v_lshrrev_b32_e32 v4, 2, v2
	v_lshlrev_b32_e32 v5, 1, v2
	v_and_b32_e32 v1, 0xc0, v1
	s_ashr_i32 s4, s0, 6
	v_and_or_b32 v3, v2, s3, v3
	v_and_b32_e32 v4, 4, v4
	v_and_b32_e32 v5, 24, v5
	v_sub_u32_e32 v0, v0, v1
	v_readlane_b32 s3, v253, 43
	s_ashr_i32 s1, s0, 8
	s_lshl_b32 s29, s4, 10
	v_or3_b32 v3, v3, v4, v5
	v_lshlrev_b32_e32 v4, 5, v13
	v_ashrrev_i16_sdwa v0, v221, sext(v0) dst_sel:DWORD dst_unused:UNUSED_PAD src0_sel:DWORD src1_sel:BYTE_0
	v_mul_lo_u32 v1, v2, s2
	s_mul_i32 s2, s3, 0x160000
	v_and_b32_e32 v14, 32, v4
	v_bfe_i32 v15, v0, 0, 16
	s_add_u32 s24, s10, s2
	s_mul_hi_i32 s2, s3, 0x160000
	v_mul_u32_u24_e32 v3, 0xb00, v3
	v_add_u32_e32 v0, v14, v15
	s_addc_u32 s25, s11, s2
	s_add_i32 s30, s29, 0
	v_add_lshl_u32 v184, v3, v0, 1
	s_add_i32 m0, s30, 0x10000
	v_add_lshl_u32 v198, v0, v1, 1
	global_load_lds_dwordx4 v184, s[24:25]
	s_add_i32 m0, s30, 0x12000
	s_add_u32 s2, s24, 0xb0000
	global_load_lds_dwordx4 v194, s[24:25]
	s_addc_u32 s3, s25, 0
	s_add_i32 m0, s30, 0x14000
	v_mov_b32_e32 v195, v185
	global_load_lds_dwordx4 v184, s[2:3]
	s_add_i32 m0, s30, 0x16000
	v_mov_b32_e32 v199, v185
	global_load_lds_dwordx4 v194, s[2:3]
	v_readlane_b32 s2, v254, 5
	s_mov_b32 s6, s2
	s_mul_i32 s2, s2, 0x18c000
	s_add_u32 s22, s8, s2
	s_mul_hi_i32 s2, s6, 0x18c000
	s_addc_u32 s23, s9, s2
	s_add_i32 s31, s30, 0x2000
	v_readlane_b32 s3, v254, 6
	s_mov_b32 m0, s30
	s_add_u32 s2, s22, 0xb0000
	global_load_lds_dwordx4 v198, s[22:23]
	s_mov_b32 m0, s31
	s_addc_u32 s3, s23, 0
	s_add_i32 s34, s30, 0x4000
	global_load_lds_dwordx4 v196, s[22:23]
	s_mul_i32 s98, s1, 0x2c000
	s_sub_u32 s98, 0x160000, s98
	v_add_u32_e32 v248, s98, v198
	s_and_b32 m0, s30, 0xc00
	s_add_i32 m0, m0, 0x20800
	s_nop 0
	global_load_lds_dwordx4 v248, s[22:23]
	s_mov_b32 m0, s34
	s_add_i32 s40, s30, 0x6000
	global_load_lds_dwordx4 v198, s[2:3]
	s_mov_b32 m0, s40
	v_mov_b32_e32 v197, v185
	global_load_lds_dwordx4 v196, s[2:3]
	s_cmp_eq_u32 s1, 1
	v_lshl_add_u64 v[6:7], s[24:25], 0, v[184:185]
	v_lshl_add_u64 v[4:5], s[24:25], 0, v[194:195]
	v_lshl_add_u64 v[0:1], s[22:23], 0, v[198:199]
	s_cselect_b64 s[2:3], -1, 0
	s_cmp_lg_u32 s1, 1
	v_lshl_add_u64 v[2:3], s[22:23], 0, v[196:197]
	s_cbranch_scc1 .LBB0_447
	s_barrier
.LBB0_447:
	v_bfe_u32 v17, v16, 4, 2
	v_and_b32_e32 v18, 15, v16
	v_lshlrev_b32_e32 v20, 4, v17
	v_lshlrev_b32_e32 v16, 2, v16
	s_and_b32 s6, s4, 3
	v_lshl_or_b32 v227, s1, 6, v18
	v_lshl_or_b32 v18, v18, 6, v20
	s_lshl_b32 s1, s1, 13
	v_and_b32_e32 v16, 32, v16
	s_add_i32 m0, s30, 0x18000
	v_lshl_add_u64 v[6:7], v[6:7], 0, s[96:97]
	v_bitop3_b32 v20, v18, s1, v16 bitop3:0xde
	s_lshl_b32 s1, s6, 12
	s_waitcnt vmcnt(2)
	s_barrier
	global_load_lds_dwordx4 v[6:7], off
	v_lshl_add_u64 v[4:5], v[4:5], 0, s[96:97]
	s_add_i32 m0, s30, 0x1a000
	s_add_i32 s41, s30, 0x8000
	s_add_i32 s42, s30, 0xa000
	global_load_lds_dwordx4 v[4:5], off
	v_lshl_add_u64 v[0:1], v[0:1], 0, s[96:97]
	s_mov_b32 m0, s41
	s_add_u32 s4, s24, 0xb0080
	global_load_lds_dwordx4 v[0:1], off
	v_lshl_add_u64 v[0:1], v[2:3], 0, s[96:97]
	s_mov_b32 m0, s42
	s_addc_u32 s5, s25, 0
	global_load_lds_dwordx4 v[0:1], off
	s_add_i32 m0, s30, 0x1c000
	v_lshl_add_u64 v[0:1], s[4:5], 0, v[184:185]
	global_load_lds_dwordx4 v[0:1], off
	v_lshl_add_u64 v[0:1], s[4:5], 0, v[194:195]
	s_add_i32 m0, s30, 0x1e000
	s_cmpk_lt_u32 s0, 0x100
	global_load_lds_dwordx4 v[0:1], off
	s_cselect_b64 s[16:17], -1, 0
	s_add_u32 s98, s22, 0x80
	s_addc_u32 s99, s23, 0
	s_and_b32 m0, s30, 0xc00
	s_add_i32 m0, m0, 0x21800
	s_nop 0
	global_load_lds_dwordx4 v248, s[98:99]
	s_add_u32 s12, s48, 0x5d00000
	s_addc_u32 s13, s49, 0
	s_add_u32 s14, s48, 0x8600000
	s_movk_i32 s4, 0xb00
	s_addc_u32 s15, s49, 0
	s_lshl_b32 s0, s6, 2
	v_lshrrev_b32_e32 v1, 1, v13
	v_mul_lo_u32 v0, v12, s4
	s_mov_b32 s5, 0xb000
	v_bitop3_b32 v228, v18, s1, v16 bitop3:0xde
	s_add_u32 s44, s14, s0
	v_mad_u64_u32 v[0:1], s[0:1], v1, s5, v[0:1]
	v_or_b32_e32 v0, v0, v14
	v_add_lshl_u32 v0, v0, v15, 1
	v_mov_b32_e32 v1, v185
	s_mov_b64 s[18:19], 0xb0080
	v_lshl_add_u64 v[200:201], v[0:1], 0, s[18:19]
	v_lshrrev_b32_e32 v1, 1, v8
	v_mul_lo_u32 v0, v9, s4
	v_mad_u64_u32 v[0:1], s[0:1], v1, s5, v[0:1]
	s_waitcnt vmcnt(7)
	v_or_b32_e32 v0, v0, v10
	v_lshlrev_b32_e32 v19, 3, v17
	v_add_lshl_u32 v0, v0, v11, 1
	v_mov_b32_e32 v1, v185
	v_readlane_b32 s0, v254, 5
	v_lshl_or_b32 v229, s6, 5, v19
	s_mov_b32 s43, 0
	v_cmp_eq_u32_e64 s[36:37], 0, v17
	s_addc_u32 s45, s15, 0
	v_lshl_add_u64 v[202:203], v[0:1], 0, s[18:19]
	v_add_u32_e32 v230, 0, v20
	s_lshr_b32 s98, s30, 12
	s_mul_i32 s98, s98, 0x1800
	s_sub_u32 s98, 0x20800, s98
	v_add_u32_e32 v249, s98, v230
	v_readlane_b32 s49, v253, 43
	s_mov_b32 s48, s0
	s_barrier
	v_readlane_b32 s1, v254, 6
	s_branch .LBB0_450

; template <class Epi, class Sched, bool ALIGN_EPI = false, bool SP2 = false>
; __device__ __forceinline__ void gemm_phase(PG8_LAS unsigned char* lds, const Gemm g, const Sched& S, const Epi& E) {
;     ...
;         const bool has_next = S.next(ui + 1, nxt);
;         const char* nA = has_next ? (const char*)g.A + (size_t)nxt.pm * tstep : cA; const char* nB = has_next ? (const char*)g.Bt + (size_t)nxt.pn * tstep : cB;
.LBB0_456:
	s_nop 0
	v_cndmask_b32_e64 v0, 0, 1, s[0:1]
	v_cmp_ne_u32_e64 s[38:39], 1, v0
	s_andn2_b64 vcc, exec, s[0:1]
	s_mov_b64 s[18:19], s[22:23]
	s_cbranch_vccnz .LBB0_458
	s_mul_i32 s1, s47, 0x18c000
	s_mul_hi_i32 s0, s47, 0x18c000
	s_add_u32 s18, s8, s1
	s_addc_u32 s19, s9, s0

; #define PG8_STAGE(bufoff, gbase, voff) do { _Pragma("unroll") for (int _i = 0; _i < 2; ++_i) \
;         __builtin_amdgcn_global_load_lds((const unsigned*)((const char*)(gbase) + (voff)[_i]), (PG8_LAS unsigned*)(lds + (bufoff) + ldsw + _i * 8192), 16, 0, 0); } while (0)
; #define PG8_LDA(dst, b, h) do { _Pragma("unroll") for (int m = 0; m < 4; ++m) _Pragma("unroll") for (int k = 0; k < 2; ++k) dst[m][k] = *(const PG8_LAS bf16x8*)(lds + PG8_SA(b, h) + aoff + m * 2048 + k * 1024); } while (0)
; #define PG8_LDB(dst, b, h) do { _Pragma("unroll") for (int n = 0; n < 2; ++n) _Pragma("unroll") for (int k = 0; k < 2; ++k) dst[n][k] = *(const PG8_LAS bf16x8*)(lds + PG8_SB(b, h) + boff + n * 2048 + k * 1024); } while (0)
; #define PG8_MMA(ai, bj, At, Bt) do { __builtin_amdgcn_s_setprio(1); _Pragma("unroll") for (int m = 0; m < 4; ++m) _Pragma("unroll") for (int n = 0; n < 2; ++n) _Pragma("unroll") for (int k = 0; k < 2; ++k) \
;         acc[ai][bj][m][n] = __builtin_amdgcn_mfma_f32_16x16x32_bf16(Bt[n][k], At[m][k], acc[ai][bj][m][n], 0, 0, 0); __builtin_amdgcn_s_setprio(0); } while (0)
; #define PG8_WAIT_V(n) asm volatile("s_waitcnt vmcnt(" #n ")" ::: "memory")
; #define PG8_BAR __builtin_amdgcn_s_barrier()
; template <class Epi, class Sched, bool ALIGN_EPI = false, bool SP2 = false>
; __device__ __forceinline__ void gemm_phase(PG8_LAS unsigned char* lds, const Gemm g, const Sched& S, const Epi& E) {
;     ...
;         for (int t = 0; t < nt; t += 2) {
;             const bool last = (t == nt - 2);
;             const char* a1 = cA + (size_t)(t + 1) * kstep;
;             const char* a2 = last ? nA : cA + (size_t)(t + 2) * kstep; const char* b2 = last ? nB : cB + (size_t)(t + 2) * kstep;
;             const char* a3 = a2 + kstep; const char* b3 = b2 + kstep;
;             if (last && has_next) S.a_ready(nxt);
;             if constexpr (SP2) {
;             PG8_LDB(B0, 0, 0); PG8_LDB(B1, 0, 1); PG8_SCHED; PG8_LDA(At, 0, 0); PG8_STAGE(PG8_SA(1, 1), a1 + hstep, voffA);
;             PG8_WAIT_V(8); PG8_WAIT_L(0); PG8_BAR; PG8_MMA(0, 0, At, B0); PG8_MMA(0, 1, At, B1); PG8_BAR; PG8_SCHED;
;     ...
;         for (int a = 0; a < 2; ++a)
; #pragma unroll
;             for (int b = 0; b < 2; ++b)
; #pragma unroll
;                 for (int m = 0; m < 4; ++m)
; #pragma unroll
;                     for (int n = 0; n < 2; ++n) acc[a][b][m][n] = (f32x4){0.f, 0.f, 0.f, 0.f};
.LBB0_460:
	s_add_u32 s4, s24, 0x100
	v_mov_b32_e32 v0, 0
	s_addc_u32 s5, s25, 0
	s_mov_b32 s50, -2
	s_waitcnt lgkmcnt(0)
	v_mov_b32_e32 v1, v0
	v_mov_b32_e32 v2, v0
	v_mov_b32_e32 v3, v0
	v_mov_b32_e32 v4, v0
	v_mov_b32_e32 v5, v0
	v_mov_b32_e32 v6, v0
	v_mov_b32_e32 v7, v0
	v_mov_b32_e32 v16, v0
	v_mov_b32_e32 v17, v0
	v_mov_b32_e32 v18, v0
	v_mov_b32_e32 v19, v0
	v_mov_b32_e32 v20, v0
	v_mov_b32_e32 v21, v0
	v_mov_b32_e32 v22, v0
	v_mov_b32_e32 v23, v0
	v_mov_b32_e32 v32, v0
	v_mov_b32_e32 v33, v0
	v_mov_b32_e32 v34, v0
	v_mov_b32_e32 v35, v0
	v_mov_b32_e32 v36, v0
	v_mov_b32_e32 v37, v0
	v_mov_b32_e32 v38, v0
	v_mov_b32_e32 v39, v0
	v_mov_b32_e32 v48, v0
	v_mov_b32_e32 v49, v0
	v_mov_b32_e32 v50, v0
	v_mov_b32_e32 v51, v0
	v_mov_b32_e32 v52, v0
	v_mov_b32_e32 v53, v0
	v_mov_b32_e32 v54, v0
	v_mov_b32_e32 v55, v0
	v_mov_b32_e32 v8, v0
	v_mov_b32_e32 v9, v0
	v_mov_b32_e32 v10, v0
	v_mov_b32_e32 v11, v0
	v_mov_b32_e32 v12, v0
	v_mov_b32_e32 v13, v0
	v_mov_b32_e32 v14, v0
	v_mov_b32_e32 v15, v0
	v_mov_b32_e32 v24, v0
	v_mov_b32_e32 v25, v0
	v_mov_b32_e32 v26, v0
	v_mov_b32_e32 v27, v0
	v_mov_b32_e32 v28, v0
	v_mov_b32_e32 v29, v0
	v_mov_b32_e32 v30, v0
	v_mov_b32_e32 v31, v0
	v_mov_b32_e32 v40, v0
	v_mov_b32_e32 v41, v0
	v_mov_b32_e32 v42, v0
	v_mov_b32_e32 v43, v0
	v_mov_b32_e32 v44, v0
	v_mov_b32_e32 v45, v0
	v_mov_b32_e32 v46, v0
	v_mov_b32_e32 v47, v0
	v_mov_b32_e32 v56, v0
	v_mov_b32_e32 v57, v0
	v_mov_b32_e32 v58, v0
	v_mov_b32_e32 v59, v0
	v_mov_b32_e32 v60, v0
	v_mov_b32_e32 v61, v0
	v_mov_b32_e32 v62, v0
	v_mov_b32_e32 v63, v0
	v_mov_b32_e32 v64, v0
	v_mov_b32_e32 v65, v0
	v_mov_b32_e32 v66, v0
	v_mov_b32_e32 v67, v0
	v_mov_b32_e32 v68, v0
	v_mov_b32_e32 v69, v0
	v_mov_b32_e32 v70, v0
	v_mov_b32_e32 v71, v0
	v_mov_b32_e32 v80, v0
	v_mov_b32_e32 v81, v0
	v_mov_b32_e32 v82, v0
	v_mov_b32_e32 v83, v0
	v_mov_b32_e32 v84, v0
	v_mov_b32_e32 v85, v0
	v_mov_b32_e32 v86, v0
	v_mov_b32_e32 v87, v0
	v_mov_b32_e32 v96, v0
	v_mov_b32_e32 v97, v0
	v_mov_b32_e32 v98, v0
	v_mov_b32_e32 v99, v0
	v_mov_b32_e32 v100, v0
	v_mov_b32_e32 v101, v0
	v_mov_b32_e32 v102, v0
	v_mov_b32_e32 v103, v0
	v_mov_b32_e32 v112, v0
	v_mov_b32_e32 v113, v0
	v_mov_b32_e32 v114, v0
	v_mov_b32_e32 v115, v0
	v_mov_b32_e32 v116, v0
	v_mov_b32_e32 v117, v0
	v_mov_b32_e32 v118, v0
	v_mov_b32_e32 v119, v0
	v_mov_b32_e32 v72, v0
	v_mov_b32_e32 v73, v0
	v_mov_b32_e32 v74, v0
	v_mov_b32_e32 v75, v0
	v_mov_b32_e32 v76, v0
	v_mov_b32_e32 v77, v0
	v_mov_b32_e32 v78, v0
	v_mov_b32_e32 v79, v0
	v_mov_b32_e32 v88, v0
	v_mov_b32_e32 v89, v0
	v_mov_b32_e32 v90, v0
	v_mov_b32_e32 v91, v0
	v_mov_b32_e32 v92, v0
	v_mov_b32_e32 v93, v0
	v_mov_b32_e32 v94, v0
	v_mov_b32_e32 v95, v0
	v_mov_b32_e32 v104, v0
	v_mov_b32_e32 v105, v0
	v_mov_b32_e32 v106, v0
	v_mov_b32_e32 v107, v0
	v_mov_b32_e32 v108, v0
	v_mov_b32_e32 v109, v0
	v_mov_b32_e32 v110, v0
	v_mov_b32_e32 v111, v0
	v_mov_b32_e32 v120, v0
	v_mov_b32_e32 v121, v0
	v_mov_b32_e32 v122, v0
	v_mov_b32_e32 v123, v0
	v_mov_b32_e32 v124, v0
	v_mov_b32_e32 v125, v0
	v_mov_b32_e32 v126, v0
	v_mov_b32_e32 v127, v0
	v_mov_b32_e32 v236, v0
	v_mov_b32_e32 v237, v0
	v_mov_b32_e32 v238, v0
	v_mov_b32_e32 v239, v0
	v_mov_b32_e32 v240, v0
	v_mov_b32_e32 v241, v0
	v_mov_b32_e32 v242, v0
	v_mov_b32_e32 v243, v0
	v_mov_b32_e32 v244, v0
	v_mov_b32_e32 v245, v0
	v_mov_b32_e32 v246, v0
	v_mov_b32_e32 v247, v0
	v_mov_b32_e32 v200, v0
	v_mov_b32_e32 v201, v0
	v_mov_b32_e32 v202, v0
	v_mov_b32_e32 v203, v0
.LBB0_461:
	s_add_u32 s0, s22, 0x100
	s_addc_u32 s1, s23, 0
	s_cmp_eq_u32 s50, 40
	s_cselect_b32 s27, s19, s1
	s_cselect_b32 s26, s18, s0
	s_cselect_b32 s25, s21, s5
	s_cselect_b32 s24, s20, s4
	s_add_i32 s6, 0, 0x10000
	s_add_i32 s51, 0, 0x14000
	v_add_u32_e32 v140, s6, v228
	v_add_u32_e32 v156, s51, v228
	ds_read_b128 v[128:131], v140
	ds_read_b128 v[132:135], v140 offset:1024
	ds_read_b128 v[136:139], v140 offset:2048
	ds_read_b128 v[140:143], v140 offset:3072
	ds_read_b128 v[144:147], v156
	ds_read_b128 v[148:151], v156 offset:1024
	ds_read_b128 v[152:155], v156 offset:2048
	ds_read_b128 v[156:159], v156 offset:3072
	s_add_u32 s98, s22, 0xb0080
	s_addc_u32 s99, s23, 0
	s_add_i32 m0, s30, 0xc000
	ds_read_b128 v[160:163], v230
	ds_read_b128 v[164:167], v230 offset:1024
	ds_read_b128 v[168:171], v230 offset:2048
	ds_read_b128 v[172:175], v230 offset:3072
	ds_read_b128 v[176:179], v230 offset:4096
	ds_read_b128 v[180:183], v230 offset:5120
	ds_read_b128 v[204:207], v230 offset:6144
	ds_read_b128 v[208:211], v230 offset:7168
	ds_read_b128 v[212:215], v249
	ds_read_b128 v[232:235], v249 offset:1024
	global_load_lds_dwordx4 v198, s[98:99]
	s_add_i32 m0, s30, 0xe000
	s_nop 0
	global_load_lds_dwordx4 v196, s[98:99]
	s_waitcnt vmcnt(9)
	s_waitcnt lgkmcnt(0)
	s_barrier
; #define PG8_STAGE(bufoff, gbase, voff) do { _Pragma("unroll") for (int _i = 0; _i < 2; ++_i) \
;         __builtin_amdgcn_global_load_lds((const unsigned*)((const char*)(gbase) + (voff)[_i]), (PG8_LAS unsigned*)(lds + (bufoff) + ldsw + _i * 8192), 16, 0, 0); } while (0)
; #define PG8_LDA(dst, b, h) do { _Pragma("unroll") for (int m = 0; m < 4; ++m) _Pragma("unroll") for (int k = 0; k < 2; ++k) dst[m][k] = *(const PG8_LAS bf16x8*)(lds + PG8_SA(b, h) + aoff + m * 2048 + k * 1024); } while (0)
; #define PG8_MMA(ai, bj, At, Bt) do { __builtin_amdgcn_s_setprio(1); _Pragma("unroll") for (int m = 0; m < 4; ++m) _Pragma("unroll") for (int n = 0; n < 2; ++n) _Pragma("unroll") for (int k = 0; k < 2; ++k) \
;         acc[ai][bj][m][n] = __builtin_amdgcn_mfma_f32_16x16x32_bf16(Bt[n][k], At[m][k], acc[ai][bj][m][n], 0, 0, 0); __builtin_amdgcn_s_setprio(0); } while (0)
; #define PG8_WAIT_V(n) asm volatile("s_waitcnt vmcnt(" #n ")" ::: "memory")
; #define PG8_WAIT_L(n) asm volatile("s_waitcnt lgkmcnt(" #n ")" ::: "memory")
; #define PG8_BAR __builtin_amdgcn_s_barrier()
; #define PG8_SCHED __builtin_amdgcn_sched_barrier(0)
; template <class Epi, class Sched, bool ALIGN_EPI = false, bool SP2 = false>
; __device__ __forceinline__ void gemm_phase(PG8_LAS unsigned char* lds, const Gemm g, const Sched& S, const Epi& E) {
;     ...
;             PG8_WAIT_V(8); PG8_WAIT_L(0); PG8_BAR; PG8_MMA(0, 0, At, B0); PG8_MMA(0, 1, At, B1); PG8_BAR; PG8_SCHED;
;             PG8_LDA(At, 0, 1); PG8_STAGE(PG8_SB(0, 0), b2, voffB); PG8_STAGE(PG8_SB(0, 1), b2 + hstep, voffB); PG8_STAGE(PG8_SA(0, 0), a2, voffA);
;             PG8_WAIT_V(8); PG8_WAIT_L(0); PG8_BAR; PG8_MMA(1, 0, At, B0); PG8_MMA(1, 1, At, B1); PG8_BAR; PG8_SCHED;
	s_setprio 1
	s_waitcnt lgkmcnt(0)
	v_mfma_f32_16x16x32_bf16 v[124:127], v[128:131], v[160:163], v[124:127]
	v_mfma_f32_16x16x32_bf16 v[120:123], v[136:139], v[160:163], v[120:123]
	v_mfma_f32_16x16x32_bf16 v[108:111], v[128:131], v[168:171], v[108:111]
	v_mfma_f32_16x16x32_bf16 v[104:107], v[136:139], v[168:171], v[104:107]
	v_mfma_f32_16x16x32_bf16 v[92:95], v[128:131], v[176:179], v[92:95]
	v_mfma_f32_16x16x32_bf16 v[88:91], v[136:139], v[176:179], v[88:91]
	v_mfma_f32_16x16x32_bf16 v[76:79], v[128:131], v[204:207], v[76:79]
	v_mfma_f32_16x16x32_bf16 v[72:75], v[136:139], v[204:207], v[72:75]
	v_mfma_f32_16x16x32_bf16 v[124:127], v[132:135], v[164:167], v[124:127]
	v_mfma_f32_16x16x32_bf16 v[120:123], v[140:143], v[164:167], v[120:123]
	v_mfma_f32_16x16x32_bf16 v[108:111], v[132:135], v[172:175], v[108:111]
	v_mfma_f32_16x16x32_bf16 v[104:107], v[140:143], v[172:175], v[104:107]
	v_mfma_f32_16x16x32_bf16 v[92:95], v[132:135], v[180:183], v[92:95]
	v_mfma_f32_16x16x32_bf16 v[88:91], v[140:143], v[180:183], v[88:91]
	v_mfma_f32_16x16x32_bf16 v[76:79], v[132:135], v[208:211], v[76:79]
	v_mfma_f32_16x16x32_bf16 v[72:75], v[140:143], v[208:211], v[72:75]
	s_setprio 0
	s_setprio 1
	v_mfma_f32_16x16x32_bf16 v[116:119], v[144:147], v[160:163], v[116:119]
	v_mfma_f32_16x16x32_bf16 v[112:115], v[152:155], v[160:163], v[112:115]
	v_mfma_f32_16x16x32_bf16 v[100:103], v[144:147], v[168:171], v[100:103]
	v_mfma_f32_16x16x32_bf16 v[96:99], v[152:155], v[168:171], v[96:99]
	v_mfma_f32_16x16x32_bf16 v[84:87], v[144:147], v[176:179], v[84:87]
	v_mfma_f32_16x16x32_bf16 v[80:83], v[152:155], v[176:179], v[80:83]
	v_mfma_f32_16x16x32_bf16 v[68:71], v[144:147], v[204:207], v[68:71]
	v_mfma_f32_16x16x32_bf16 v[64:67], v[152:155], v[204:207], v[64:67]
	v_mfma_f32_16x16x32_bf16 v[116:119], v[148:151], v[164:167], v[116:119]
	v_mfma_f32_16x16x32_bf16 v[112:115], v[156:159], v[164:167], v[112:115]
	v_mfma_f32_16x16x32_bf16 v[100:103], v[148:151], v[172:175], v[100:103]
	v_mfma_f32_16x16x32_bf16 v[96:99], v[156:159], v[172:175], v[96:99]
	v_mfma_f32_16x16x32_bf16 v[84:87], v[148:151], v[180:183], v[84:87]
	v_mfma_f32_16x16x32_bf16 v[80:83], v[156:159], v[180:183], v[80:83]
	v_mfma_f32_16x16x32_bf16 v[68:71], v[148:151], v[208:211], v[68:71]
	v_mfma_f32_16x16x32_bf16 v[64:67], v[156:159], v[208:211], v[64:67]
	v_mfma_f32_16x16x32_bf16 v[236:239], v[128:131], v[212:215], v[236:239]
	v_mfma_f32_16x16x32_bf16 v[240:243], v[136:139], v[212:215], v[240:243]
	v_mfma_f32_16x16x32_bf16 v[244:247], v[144:147], v[212:215], v[244:247]
	v_mfma_f32_16x16x32_bf16 v[200:203], v[152:155], v[212:215], v[200:203]
	v_mfma_f32_16x16x32_bf16 v[236:239], v[132:135], v[232:235], v[236:239]
	v_mfma_f32_16x16x32_bf16 v[240:243], v[140:143], v[232:235], v[240:243]
	v_mfma_f32_16x16x32_bf16 v[244:247], v[148:151], v[232:235], v[244:247]
	v_mfma_f32_16x16x32_bf16 v[200:203], v[156:159], v[232:235], v[200:203]
	s_setprio 0
	s_barrier
	s_add_i32 s6, s6, s29
	s_mov_b32 m0, s6
	ds_read_b128 v[160:163], v230 offset:16384
	ds_read_b128 v[164:167], v230 offset:17408
	ds_read_b128 v[168:171], v230 offset:18432
	ds_read_b128 v[172:175], v230 offset:19456
	ds_read_b128 v[176:179], v230 offset:20480
	ds_read_b128 v[180:183], v230 offset:21504
	ds_read_b128 v[204:207], v230 offset:22528
	ds_read_b128 v[208:211], v230 offset:23552
	global_load_lds_dwordx4 v184, s[24:25]
	s_add_i32 m0, s6, 0x2000
	s_add_u32 s22, s24, 0xb0000
	s_addc_u32 s23, s25, 0
	s_add_i32 s6, s51, s29
	global_load_lds_dwordx4 v194, s[24:25]
	s_mov_b32 m0, s6
	s_nop 0
	global_load_lds_dwordx4 v184, s[22:23]
	s_add_i32 m0, s6, 0x2000
	s_nop 0
	global_load_lds_dwordx4 v194, s[22:23]
	s_mov_b32 m0, s30
	s_nop 0
	global_load_lds_dwordx4 v198, s[26:27]
	s_mov_b32 m0, s31
	s_nop 0
	global_load_lds_dwordx4 v196, s[26:27]
	s_and_b32 m0, s30, 0xc00
	s_add_i32 m0, m0, 0x20800
	s_nop 0
	global_load_lds_dwordx4 v248, s[26:27]
	s_waitcnt vmcnt(9)
	s_waitcnt lgkmcnt(0)
	s_barrier
	s_setprio 1
	s_waitcnt lgkmcnt(0)
	v_mfma_f32_16x16x32_bf16 v[60:63], v[128:131], v[160:163], v[60:63]
	v_mfma_f32_16x16x32_bf16 v[56:59], v[136:139], v[160:163], v[56:59]
	v_mfma_f32_16x16x32_bf16 v[44:47], v[128:131], v[168:171], v[44:47]
	v_mfma_f32_16x16x32_bf16 v[40:43], v[136:139], v[168:171], v[40:43]
	v_mfma_f32_16x16x32_bf16 v[28:31], v[128:131], v[176:179], v[28:31]
	v_mfma_f32_16x16x32_bf16 v[24:27], v[136:139], v[176:179], v[24:27]
	v_mfma_f32_16x16x32_bf16 v[12:15], v[128:131], v[204:207], v[12:15]
	v_mfma_f32_16x16x32_bf16 v[8:11], v[136:139], v[204:207], v[8:11]
	v_mfma_f32_16x16x32_bf16 v[60:63], v[132:135], v[164:167], v[60:63]
	v_mfma_f32_16x16x32_bf16 v[56:59], v[140:143], v[164:167], v[56:59]
	v_mfma_f32_16x16x32_bf16 v[44:47], v[132:135], v[172:175], v[44:47]
	v_mfma_f32_16x16x32_bf16 v[40:43], v[140:143], v[172:175], v[40:43]
	v_mfma_f32_16x16x32_bf16 v[28:31], v[132:135], v[180:183], v[28:31]
	v_mfma_f32_16x16x32_bf16 v[24:27], v[140:143], v[180:183], v[24:27]
	v_mfma_f32_16x16x32_bf16 v[12:15], v[132:135], v[208:211], v[12:15]
	v_mfma_f32_16x16x32_bf16 v[8:11], v[140:143], v[208:211], v[8:11]
	s_setprio 0
	s_setprio 1
	v_mfma_f32_16x16x32_bf16 v[52:55], v[144:147], v[160:163], v[52:55]
	v_mfma_f32_16x16x32_bf16 v[48:51], v[152:155], v[160:163], v[48:51]
	v_mfma_f32_16x16x32_bf16 v[36:39], v[144:147], v[168:171], v[36:39]
	v_mfma_f32_16x16x32_bf16 v[32:35], v[152:155], v[168:171], v[32:35]
	v_mfma_f32_16x16x32_bf16 v[20:23], v[144:147], v[176:179], v[20:23]
	v_mfma_f32_16x16x32_bf16 v[16:19], v[152:155], v[176:179], v[16:19]
	v_mfma_f32_16x16x32_bf16 v[4:7], v[144:147], v[204:207], v[4:7]
	v_mfma_f32_16x16x32_bf16 v[0:3], v[152:155], v[204:207], v[0:3]
	v_mfma_f32_16x16x32_bf16 v[52:55], v[148:151], v[164:167], v[52:55]
	v_mfma_f32_16x16x32_bf16 v[48:51], v[156:159], v[164:167], v[48:51]
	v_mfma_f32_16x16x32_bf16 v[36:39], v[148:151], v[172:175], v[36:39]
	v_mfma_f32_16x16x32_bf16 v[32:35], v[156:159], v[172:175], v[32:35]
	v_mfma_f32_16x16x32_bf16 v[20:23], v[148:151], v[180:183], v[20:23]
	v_mfma_f32_16x16x32_bf16 v[16:19], v[156:159], v[180:183], v[16:19]
	v_mfma_f32_16x16x32_bf16 v[4:7], v[148:151], v[208:211], v[4:7]
	v_mfma_f32_16x16x32_bf16 v[0:3], v[156:159], v[208:211], v[0:3]
	s_setprio 0
	s_barrier
; #define PG8_STAGE(bufoff, gbase, voff) do { _Pragma("unroll") for (int _i = 0; _i < 2; ++_i) \
;         __builtin_amdgcn_global_load_lds((const unsigned*)((const char*)(gbase) + (voff)[_i]), (PG8_LAS unsigned*)(lds + (bufoff) + ldsw + _i * 8192), 16, 0, 0); } while (0)
; #define PG8_LDA(dst, b, h) do { _Pragma("unroll") for (int m = 0; m < 4; ++m) _Pragma("unroll") for (int k = 0; k < 2; ++k) dst[m][k] = *(const PG8_LAS bf16x8*)(lds + PG8_SA(b, h) + aoff + m * 2048 + k * 1024); } while (0)
; #define PG8_LDB(dst, b, h) do { _Pragma("unroll") for (int n = 0; n < 2; ++n) _Pragma("unroll") for (int k = 0; k < 2; ++k) dst[n][k] = *(const PG8_LAS bf16x8*)(lds + PG8_SB(b, h) + boff + n * 2048 + k * 1024); } while (0)
; #define PG8_MMA(ai, bj, At, Bt) do { __builtin_amdgcn_s_setprio(1); _Pragma("unroll") for (int m = 0; m < 4; ++m) _Pragma("unroll") for (int n = 0; n < 2; ++n) _Pragma("unroll") for (int k = 0; k < 2; ++k) \
;         acc[ai][bj][m][n] = __builtin_amdgcn_mfma_f32_16x16x32_bf16(Bt[n][k], At[m][k], acc[ai][bj][m][n], 0, 0, 0); __builtin_amdgcn_s_setprio(0); } while (0)
; #define PG8_WAIT_V(n) asm volatile("s_waitcnt vmcnt(" #n ")" ::: "memory")
; #define PG8_WAIT_L(n) asm volatile("s_waitcnt lgkmcnt(" #n ")" ::: "memory")
; #define PG8_BAR __builtin_amdgcn_s_barrier()
; #define PG8_SCHED __builtin_amdgcn_sched_barrier(0)
; template <class Epi, class Sched, bool ALIGN_EPI = false, bool SP2 = false>
; __device__ __forceinline__ void gemm_phase(PG8_LAS unsigned char* lds, const Gemm g, const Sched& S, const Epi& E) {
;     ...
;             PG8_LDB(B0, 1, 0); PG8_LDB(B1, 1, 1); PG8_SCHED; PG8_LDA(At, 1, 0); PG8_STAGE(PG8_SA(0, 1), a2 + hstep, voffA);
;             PG8_WAIT_V(8); PG8_WAIT_L(0); PG8_BAR; PG8_MMA(0, 0, At, B0); PG8_MMA(0, 1, At, B1); PG8_BAR; PG8_SCHED;
;             PG8_LDA(At, 1, 1); PG8_STAGE(PG8_SB(1, 0), b3, voffB); PG8_STAGE(PG8_SB(1, 1), b3 + hstep, voffB); PG8_STAGE(PG8_SA(1, 0), a3, voffA);
	s_add_i32 s6, 0, 0x18000
	s_add_i32 s51, 0, 0x1c000
	v_add_u32_e32 v140, s6, v228
	v_add_u32_e32 v156, s51, v228
	ds_read_b128 v[128:131], v140
	ds_read_b128 v[132:135], v140 offset:1024
	ds_read_b128 v[136:139], v140 offset:2048
	ds_read_b128 v[140:143], v140 offset:3072
	ds_read_b128 v[144:147], v156
	ds_read_b128 v[148:151], v156 offset:1024
	ds_read_b128 v[152:155], v156 offset:2048
	ds_read_b128 v[156:159], v156 offset:3072
	s_add_u32 s22, s26, 0xb0000
	s_addc_u32 s23, s27, 0
	s_mov_b32 m0, s34
	ds_read_b128 v[160:163], v230 offset:32768
	ds_read_b128 v[164:167], v230 offset:33792
	ds_read_b128 v[168:171], v230 offset:34816
	ds_read_b128 v[172:175], v230 offset:35840
	ds_read_b128 v[176:179], v230 offset:36864
	ds_read_b128 v[180:183], v230 offset:37888
	ds_read_b128 v[204:207], v230 offset:38912
	ds_read_b128 v[208:211], v230 offset:39936
	ds_read_b128 v[212:215], v249 offset:4096
	ds_read_b128 v[232:235], v249 offset:5120
	global_load_lds_dwordx4 v198, s[22:23]
	s_mov_b32 m0, s40
	s_nop 0
	global_load_lds_dwordx4 v196, s[22:23]
	s_waitcnt vmcnt(9)
	s_waitcnt lgkmcnt(0)
	s_barrier
	s_setprio 1
	s_waitcnt lgkmcnt(0)
	v_mfma_f32_16x16x32_bf16 v[124:127], v[128:131], v[160:163], v[124:127]
	v_mfma_f32_16x16x32_bf16 v[120:123], v[136:139], v[160:163], v[120:123]
	v_mfma_f32_16x16x32_bf16 v[108:111], v[128:131], v[168:171], v[108:111]
	v_mfma_f32_16x16x32_bf16 v[104:107], v[136:139], v[168:171], v[104:107]
	v_mfma_f32_16x16x32_bf16 v[92:95], v[128:131], v[176:179], v[92:95]
	v_mfma_f32_16x16x32_bf16 v[88:91], v[136:139], v[176:179], v[88:91]
	v_mfma_f32_16x16x32_bf16 v[76:79], v[128:131], v[204:207], v[76:79]
	v_mfma_f32_16x16x32_bf16 v[72:75], v[136:139], v[204:207], v[72:75]
	v_mfma_f32_16x16x32_bf16 v[124:127], v[132:135], v[164:167], v[124:127]
	v_mfma_f32_16x16x32_bf16 v[120:123], v[140:143], v[164:167], v[120:123]
	v_mfma_f32_16x16x32_bf16 v[108:111], v[132:135], v[172:175], v[108:111]
	v_mfma_f32_16x16x32_bf16 v[104:107], v[140:143], v[172:175], v[104:107]
	v_mfma_f32_16x16x32_bf16 v[92:95], v[132:135], v[180:183], v[92:95]
	v_mfma_f32_16x16x32_bf16 v[88:91], v[140:143], v[180:183], v[88:91]
	v_mfma_f32_16x16x32_bf16 v[76:79], v[132:135], v[208:211], v[76:79]
	v_mfma_f32_16x16x32_bf16 v[72:75], v[140:143], v[208:211], v[72:75]
	s_setprio 0
	s_setprio 1
	v_mfma_f32_16x16x32_bf16 v[116:119], v[144:147], v[160:163], v[116:119]
	v_mfma_f32_16x16x32_bf16 v[112:115], v[152:155], v[160:163], v[112:115]
	v_mfma_f32_16x16x32_bf16 v[100:103], v[144:147], v[168:171], v[100:103]
	v_mfma_f32_16x16x32_bf16 v[96:99], v[152:155], v[168:171], v[96:99]
	v_mfma_f32_16x16x32_bf16 v[84:87], v[144:147], v[176:179], v[84:87]
	v_mfma_f32_16x16x32_bf16 v[80:83], v[152:155], v[176:179], v[80:83]
	v_mfma_f32_16x16x32_bf16 v[68:71], v[144:147], v[204:207], v[68:71]
	v_mfma_f32_16x16x32_bf16 v[64:67], v[152:155], v[204:207], v[64:67]
	v_mfma_f32_16x16x32_bf16 v[116:119], v[148:151], v[164:167], v[116:119]
	v_mfma_f32_16x16x32_bf16 v[112:115], v[156:159], v[164:167], v[112:115]
	v_mfma_f32_16x16x32_bf16 v[100:103], v[148:151], v[172:175], v[100:103]
	v_mfma_f32_16x16x32_bf16 v[96:99], v[156:159], v[172:175], v[96:99]
	v_mfma_f32_16x16x32_bf16 v[84:87], v[148:151], v[180:183], v[84:87]
	v_mfma_f32_16x16x32_bf16 v[80:83], v[156:159], v[180:183], v[80:83]
	v_mfma_f32_16x16x32_bf16 v[68:71], v[148:151], v[208:211], v[68:71]
	v_mfma_f32_16x16x32_bf16 v[64:67], v[156:159], v[208:211], v[64:67]
	v_mfma_f32_16x16x32_bf16 v[236:239], v[128:131], v[212:215], v[236:239]
	v_mfma_f32_16x16x32_bf16 v[240:243], v[136:139], v[212:215], v[240:243]
	v_mfma_f32_16x16x32_bf16 v[244:247], v[144:147], v[212:215], v[244:247]
	v_mfma_f32_16x16x32_bf16 v[200:203], v[152:155], v[212:215], v[200:203]
	v_mfma_f32_16x16x32_bf16 v[236:239], v[132:135], v[232:235], v[236:239]
	v_mfma_f32_16x16x32_bf16 v[240:243], v[140:143], v[232:235], v[240:243]
	v_mfma_f32_16x16x32_bf16 v[244:247], v[148:151], v[232:235], v[244:247]
	v_mfma_f32_16x16x32_bf16 v[200:203], v[156:159], v[232:235], v[200:203]
	s_setprio 0
	s_barrier
	s_add_i32 s22, s6, s29
	s_add_u32 s98, s24, 0x80
	s_addc_u32 s99, s25, 0
	s_mov_b32 m0, s22
	ds_read_b128 v[160:163], v230 offset:49152
	ds_read_b128 v[164:167], v230 offset:50176
	ds_read_b128 v[168:171], v230 offset:51200
	ds_read_b128 v[172:175], v230 offset:52224
	ds_read_b128 v[176:179], v230 offset:53248
	ds_read_b128 v[180:183], v230 offset:54272
	ds_read_b128 v[204:207], v230 offset:55296
	ds_read_b128 v[208:211], v230 offset:56320
	global_load_lds_dwordx4 v184, s[98:99]
	s_add_i32 m0, s22, 0x2000
	s_add_u32 s100, s24, 0xb0080
	s_addc_u32 s101, s25, 0
	s_add_i32 s22, s51, s29
	global_load_lds_dwordx4 v194, s[98:99]
	s_mov_b32 m0, s22
	s_add_u32 s98, s26, 0x80
	s_addc_u32 s99, s27, 0
	global_load_lds_dwordx4 v184, s[100:101]
	s_add_i32 m0, s22, 0x2000
	s_nop 0
	global_load_lds_dwordx4 v194, s[100:101]
	s_mov_b32 m0, s41
	s_nop 0
	global_load_lds_dwordx4 v198, s[98:99]
	s_mov_b32 m0, s42
	s_nop 0
	global_load_lds_dwordx4 v196, s[98:99]
	s_and_b32 m0, s30, 0xc00
	s_add_i32 m0, m0, 0x21800
	s_nop 0
	global_load_lds_dwordx4 v248, s[98:99]
	s_waitcnt vmcnt(9)
	s_waitcnt lgkmcnt(0)
	s_barrier
; __device__ __forceinline__ float quad_sum(float s) { s += __shfl_xor(s, 16); s += __shfl_xor(s, 32); return s; }
; __device__ __forceinline__ float sq4(const f32x4 a) { return (a[0] * a[0] + a[1] * a[1]) + (a[2] * a[2] + a[3] * a[3]); }
; __device__ __forceinline__ u32x4 pack8(const f32x4 a, const f32x4 b) { u32x4 w; w.x = cvt_pk_bf16(a[0], a[1]); w.y = cvt_pk_bf16(a[2], a[3]); w.z = cvt_pk_bf16(b[0], b[1]); w.w = cvt_pk_bf16(b[2], b[3]); return w; }
; #define PG8_WAIT_V(n) asm volatile("s_waitcnt vmcnt(" #n ")" ::: "memory")
;     __device__ __forceinline__ void operator()(const f32x4 (&acc)[2][2][4][2], const Unit& u, int wr, int wc, int fr, int fq) const {
;     ...
;         const int col0 = u.pn * BM + wc * 32 + 8 * fq;
; #pragma unroll
;         for (int ai = 0; ai < 2; ++ai) {
;             f32x4 bv[4][2][2];
; #pragma unroll
;             for (int m = 0; m < 4; ++m) {
;                 const int row = u.pm * BM + ai * HALF + wr * 64 + m * 16 + fr;
;                 const float* bp = (u.pm < 64) ? base_p + (size_t)row * 1024 : base_s + (size_t)(row - E_MP) * 1024;
; #pragma unroll
;                 for (int bj = 0; bj < 2; ++bj) { bv[m][bj][0] = *(const f32x4*)(bp + col0 + bj * HALF); bv[m][bj][1] = *(const f32x4*)(bp + col0 + bj * HALF + 4); }
;             }
; #pragma unroll
;             for (int m = 0; m < 4; ++m) {
;                 const int row = u.pm * BM + ai * HALF + wr * 64 + m * 16 + fr;
;                 float ss = 0.f;
; #pragma unroll
;                 for (int bj = 0; bj < 2; ++bj) {
;                     const int c = col0 + bj * HALF;
;                     const f32x4 y0 = bv[m][bj][0] + acc[ai][bj][m][0], y1 = bv[m][bj][1] + acc[ai][bj][m][1];
;                     float* d = out + (size_t)row * 1024 + c; *(f32x4*)d = y0; *(f32x4*)(d + 4) = y1;
;                     *(u32x4*)(AB + (size_t)row * 1024 + c) = pack8(y0, y1);
;                     ss += sq4(y0) + sq4(y1);
;                 }
;                 ss = quad_sum(ss);
;                 if (fq == 0) PS[(size_t)row * 16 + u.pn * 4 + wc] = ss;
; template <class Epi, class Sched, bool ALIGN_EPI = false, bool SP2 = false>
; __device__ __forceinline__ void gemm_phase(PG8_LAS unsigned char* lds, const Gemm g, const Sched& S, const Epi& E) {
;     ...
;             PG8_WAIT_V(8); PG8_WAIT_L(0); PG8_BAR; PG8_MMA(1, 0, At, B0); PG8_MMA(1, 1, At, B1); PG8_BAR; PG8_SCHED;
	s_setprio 1
	s_waitcnt lgkmcnt(0)
	v_mfma_f32_16x16x32_bf16 v[60:63], v[128:131], v[160:163], v[60:63]
	v_mfma_f32_16x16x32_bf16 v[56:59], v[136:139], v[160:163], v[56:59]
	v_mfma_f32_16x16x32_bf16 v[44:47], v[128:131], v[168:171], v[44:47]
	v_mfma_f32_16x16x32_bf16 v[40:43], v[136:139], v[168:171], v[40:43]
	v_mfma_f32_16x16x32_bf16 v[28:31], v[128:131], v[176:179], v[28:31]
	v_mfma_f32_16x16x32_bf16 v[24:27], v[136:139], v[176:179], v[24:27]
	v_mfma_f32_16x16x32_bf16 v[12:15], v[128:131], v[204:207], v[12:15]
	v_mfma_f32_16x16x32_bf16 v[8:11], v[136:139], v[204:207], v[8:11]
	v_mfma_f32_16x16x32_bf16 v[60:63], v[132:135], v[164:167], v[60:63]
	v_mfma_f32_16x16x32_bf16 v[56:59], v[140:143], v[164:167], v[56:59]
	v_mfma_f32_16x16x32_bf16 v[44:47], v[132:135], v[172:175], v[44:47]
	v_mfma_f32_16x16x32_bf16 v[40:43], v[140:143], v[172:175], v[40:43]
	v_mfma_f32_16x16x32_bf16 v[28:31], v[132:135], v[180:183], v[28:31]
	v_mfma_f32_16x16x32_bf16 v[24:27], v[140:143], v[180:183], v[24:27]
	v_mfma_f32_16x16x32_bf16 v[12:15], v[132:135], v[208:211], v[12:15]
	v_mfma_f32_16x16x32_bf16 v[8:11], v[140:143], v[208:211], v[8:11]
	s_setprio 0
	s_setprio 1
	v_mfma_f32_16x16x32_bf16 v[52:55], v[144:147], v[160:163], v[52:55]
	v_mfma_f32_16x16x32_bf16 v[48:51], v[152:155], v[160:163], v[48:51]
	v_mfma_f32_16x16x32_bf16 v[36:39], v[144:147], v[168:171], v[36:39]
	v_mfma_f32_16x16x32_bf16 v[32:35], v[152:155], v[168:171], v[32:35]
	v_mfma_f32_16x16x32_bf16 v[20:23], v[144:147], v[176:179], v[20:23]
	v_mfma_f32_16x16x32_bf16 v[16:19], v[152:155], v[176:179], v[16:19]
	v_mfma_f32_16x16x32_bf16 v[4:7], v[144:147], v[204:207], v[4:7]
	v_mfma_f32_16x16x32_bf16 v[0:3], v[152:155], v[204:207], v[0:3]
	v_mfma_f32_16x16x32_bf16 v[52:55], v[148:151], v[164:167], v[52:55]
	v_mfma_f32_16x16x32_bf16 v[48:51], v[156:159], v[164:167], v[48:51]
	v_mfma_f32_16x16x32_bf16 v[36:39], v[148:151], v[172:175], v[36:39]
	v_mfma_f32_16x16x32_bf16 v[32:35], v[156:159], v[172:175], v[32:35]
	v_mfma_f32_16x16x32_bf16 v[20:23], v[148:151], v[180:183], v[20:23]
	v_mfma_f32_16x16x32_bf16 v[16:19], v[156:159], v[180:183], v[16:19]
	v_mfma_f32_16x16x32_bf16 v[4:7], v[148:151], v[208:211], v[4:7]
	v_mfma_f32_16x16x32_bf16 v[0:3], v[156:159], v[208:211], v[0:3]
	s_setprio 0
	s_barrier
	s_add_i32 s50, s50, 2
	s_add_u32 s4, s4, 0x100
	s_addc_u32 s5, s5, 0
	s_cmp_gt_u32 s50, 41
	s_mov_b64 s[22:23], s[0:1]
	s_cbranch_scc0 .LBB0_461
	s_and_b64 vcc, exec, s[16:17]
	s_cbranch_vccz .LBB0_464
	s_barrier
.LBB0_464:
	s_mul_i32 s98, s48, 0x120
	v_and_b32_e32 v128, 15, v227
	v_lshrrev_b32_e32 v129, 6, v227
	v_lshl_add_u32 v128, v129, 4, v128
	v_add_u32_e32 v128, s98, v128
	v_add_u32_e32 v128, 0x100, v128
	v_mov_b32_e32 v129, 0
	v_lshl_or_b32 v130, s49, 8, v229
	v_mov_b32_e32 v131, 0
	v_lshlrev_b64 v[132:133], 12, v[128:129]
	v_lshl_add_u64 v[132:133], s[74:75], 0, v[132:133]
	v_lshl_add_u64 v[132:133], v[130:131], 2, v[132:133]
	global_load_dwordx4 v[136:139], v[132:133], off
	global_load_dwordx4 v[140:143], v[132:133], off offset:16
	global_load_dwordx4 v[144:147], v[132:133], off offset:512
	global_load_dwordx4 v[148:151], v[132:133], off offset:528
	v_lshlrev_b64 v[134:135], 11, v[128:129]
	v_lshl_add_u64 v[134:135], s[12:13], 0, v[134:135]
	v_lshl_add_u64 v[134:135], v[130:131], 1, v[134:135]
	s_lshl_b32 s98, s49, 4
	s_add_u32 s98, s44, s98
	s_addc_u32 s99, s45, 0
	v_lshlrev_b64 v[164:165], 6, v[128:129]
	v_lshl_add_u64 v[164:165], s[98:99], 0, v[164:165]
	v_xor_b32_e32 v162, 16, v222
	v_lshlrev_b32_e32 v162, 2, v162
	v_xor_b32_e32 v163, 32, v222
	v_lshlrev_b32_e32 v163, 2, v163
	s_waitcnt vmcnt(0)
	v_pk_add_f32 v[136:137], v[236:237], v[136:137]
	v_pk_add_f32 v[138:139], v[238:239], v[138:139]
	v_pk_add_f32 v[140:141], v[240:241], v[140:141]
	v_pk_add_f32 v[142:143], v[242:243], v[142:143]
	v_pk_add_f32 v[144:145], v[244:245], v[144:145]
	v_pk_add_f32 v[146:147], v[246:247], v[146:147]
	v_pk_add_f32 v[148:149], v[200:201], v[148:149]
	v_pk_add_f32 v[150:151], v[202:203], v[150:151]
	global_store_dwordx4 v[132:133], v[136:139], off
	global_store_dwordx4 v[132:133], v[140:143], off offset:16
	global_store_dwordx4 v[132:133], v[144:147], off offset:512
	global_store_dwordx4 v[132:133], v[148:151], off offset:528
	v_cvt_pk_bf16_f32 v152, v136, v137
	v_cvt_pk_bf16_f32 v153, v138, v139
	v_cvt_pk_bf16_f32 v154, v140, v141
	v_cvt_pk_bf16_f32 v155, v142, v143
	v_cvt_pk_bf16_f32 v156, v144, v145
	v_cvt_pk_bf16_f32 v157, v146, v147
	v_cvt_pk_bf16_f32 v158, v148, v149
	v_cvt_pk_bf16_f32 v159, v150, v151
	global_store_dwordx4 v[134:135], v[152:155], off
	global_store_dwordx4 v[134:135], v[156:159], off offset:256
	v_mul_f32_e32 v160, v136, v136
	v_fmac_f32_e32 v160, v137, v137
	v_fmac_f32_e32 v160, v138, v138
	v_fmac_f32_e32 v160, v139, v139
	v_fmac_f32_e32 v160, v140, v140
	v_fmac_f32_e32 v160, v141, v141
	v_fmac_f32_e32 v160, v142, v142
	v_fmac_f32_e32 v160, v143, v143
	v_fmac_f32_e32 v160, v144, v144
	v_fmac_f32_e32 v160, v145, v145
	v_fmac_f32_e32 v160, v146, v146
	v_fmac_f32_e32 v160, v147, v147
	v_fmac_f32_e32 v160, v148, v148
	v_fmac_f32_e32 v160, v149, v149
	v_fmac_f32_e32 v160, v150, v150
	v_fmac_f32_e32 v160, v151, v151
	ds_bpermute_b32 v161, v162, v160
	s_waitcnt lgkmcnt(0)
	v_add_f32_e32 v160, v160, v161
	ds_bpermute_b32 v161, v163, v160
	s_waitcnt lgkmcnt(0)
; __device__ __forceinline__ float quad_sum(float s) { s += __shfl_xor(s, 16); s += __shfl_xor(s, 32); return s; }
; __device__ __forceinline__ float sq4(const f32x4 a) { return (a[0] * a[0] + a[1] * a[1]) + (a[2] * a[2] + a[3] * a[3]); }
; __device__ __forceinline__ u32x4 pack8(const f32x4 a, const f32x4 b) { u32x4 w; w.x = cvt_pk_bf16(a[0], a[1]); w.y = cvt_pk_bf16(a[2], a[3]); w.z = cvt_pk_bf16(b[0], b[1]); w.w = cvt_pk_bf16(b[2], b[3]); return w; }
;     __device__ __forceinline__ void operator()(const f32x4 (&acc)[2][2][4][2], const Unit& u, int wr, int wc, int fr, int fq) const {
;         bf16_t* AB = (bf16_t*)(ws + WS_AB); float* PS = (float*)(ws + WS_PS);
;         const int col0 = u.pn * BM + wc * 32 + 8 * fq;
; #pragma unroll
;         for (int ai = 0; ai < 2; ++ai) {
;             f32x4 bv[4][2][2];
; #pragma unroll
;             for (int m = 0; m < 4; ++m) {
;                 const int row = u.pm * BM + ai * HALF + wr * 64 + m * 16 + fr;
;                 const float* bp = (u.pm < 64) ? base_p + (size_t)row * 1024 : base_s + (size_t)(row - E_MP) * 1024;
; #pragma unroll
;                 for (int bj = 0; bj < 2; ++bj) { bv[m][bj][0] = *(const f32x4*)(bp + col0 + bj * HALF); bv[m][bj][1] = *(const f32x4*)(bp + col0 + bj * HALF + 4); }
;             }
; #pragma unroll
;             for (int m = 0; m < 4; ++m) {
;                 const int row = u.pm * BM + ai * HALF + wr * 64 + m * 16 + fr;
;                 float ss = 0.f;
; #pragma unroll
;                 for (int bj = 0; bj < 2; ++bj) {
;                     const int c = col0 + bj * HALF;
;                     const f32x4 y0 = bv[m][bj][0] + acc[ai][bj][m][0], y1 = bv[m][bj][1] + acc[ai][bj][m][1];
;                     float* d = out + (size_t)row * 1024 + c; *(f32x4*)d = y0; *(f32x4*)(d + 4) = y1;
;                     *(u32x4*)(AB + (size_t)row * 1024 + c) = pack8(y0, y1);
;                     ss += sq4(y0) + sq4(y1);
;                 }
;                 ss = quad_sum(ss);
;                 if (fq == 0) PS[(size_t)row * 16 + u.pn * 4 + wc] = ss;
	v_add_f32_e32 v160, v160, v161
	s_and_saveexec_b64 s[98:99], s[36:37]
	global_store_dword v[164:165], v160, off
	s_or_b64 exec, exec, s[98:99]
	s_lshl_b32 s0, s49, 2
	s_ashr_i32 s1, s0, 31
	s_lshl_b64 s[0:1], s[0:1], 2
	s_add_u32 s22, s44, s0
	s_addc_u32 s23, s45, s1
	s_mul_i32 s98, s48, 0x120
	v_add_u32_e32 v208, s98, v227
	s_cmp_eq_u32 s48, s48
	s_cselect_b64 vcc, -1, 0
	v_add_u32_e32 v128, 0xffffc000, v208
	v_cndmask_b32_e32 v128, v128, v208, vcc
	v_lshl_or_b32 v204, s49, 8, v229
	s_and_b64 s[0:1], vcc, exec
	v_ashrrev_i32_e32 v129, 31, v128
	v_ashrrev_i32_e32 v205, 31, v204
	s_cselect_b32 s25, s75, s57
	s_cselect_b32 s24, s74, s56
	v_lshlrev_b64 v[128:129], 12, v[128:129]
	v_lshl_add_u64 v[128:129], s[24:25], 0, v[128:129]
	v_lshlrev_b64 v[206:207], 2, v[204:205]
	v_lshl_add_u64 v[128:129], v[128:129], 0, v[206:207]
	global_load_dwordx4 v[232:235], v[128:129], off offset:16
	global_load_dwordx4 v[236:239], v[128:129], off
	global_load_dwordx4 v[176:179], v[128:129], off offset:528
	global_load_dwordx4 v[180:183], v[128:129], off offset:512
	v_add_u32_e32 v214, 16, v208
	v_add_u32_e32 v128, 0xffffc010, v208
	v_cndmask_b32_e32 v128, v128, v214, vcc
	v_ashrrev_i32_e32 v129, 31, v128
	v_lshlrev_b64 v[128:129], 12, v[128:129]
	v_lshl_add_u64 v[128:129], s[24:25], 0, v[128:129]
	v_lshl_add_u64 v[128:129], v[128:129], 0, v[206:207]
	global_load_dwordx4 v[168:171], v[128:129], off offset:16
	global_load_dwordx4 v[172:175], v[128:129], off
	global_load_dwordx4 v[160:163], v[128:129], off offset:528
	global_load_dwordx4 v[164:167], v[128:129], off offset:512
	v_add_u32_e32 v212, 32, v208
	v_add_u32_e32 v128, 0xffffc020, v208
	v_cndmask_b32_e32 v128, v128, v212, vcc
	v_ashrrev_i32_e32 v129, 31, v128
	v_lshlrev_b64 v[128:129], 12, v[128:129]
	v_lshl_add_u64 v[128:129], s[24:25], 0, v[128:129]
	v_lshl_add_u64 v[128:129], v[128:129], 0, v[206:207]
	global_load_dwordx4 v[152:155], v[128:129], off offset:16
	global_load_dwordx4 v[156:159], v[128:129], off
	global_load_dwordx4 v[136:139], v[128:129], off offset:528
	global_load_dwordx4 v[140:143], v[128:129], off offset:512
	v_add_u32_e32 v210, 48, v208
	v_add_u32_e32 v128, 0xffffc030, v208
	v_cndmask_b32_e32 v128, v128, v210, vcc
	v_ashrrev_i32_e32 v129, 31, v128
	v_lshlrev_b64 v[128:129], 12, v[128:129]
	v_lshl_add_u64 v[128:129], s[24:25], 0, v[128:129]
	v_lshl_add_u64 v[132:133], v[128:129], 0, v[206:207]
	global_load_dwordx4 v[144:147], v[132:133], off offset:16
	global_load_dwordx4 v[148:151], v[132:133], off
	global_load_dwordx4 v[128:131], v[132:133], off offset:528
	s_nop 0
	global_load_dwordx4 v[132:135], v[132:133], off offset:512
	v_ashrrev_i32_e32 v209, 31, v208
	v_lshlrev_b64 v[224:225], 11, v[208:209]
	v_lshl_add_u64 v[224:225], s[12:13], 0, v[224:225]
	v_lshl_add_u64 v[224:225], v[204:205], 1, v[224:225]
	s_waitcnt vmcnt(0)
	v_pk_add_f32 v[120:121], v[120:121], v[232:233]
	v_lshlrev_b64 v[232:233], 12, v[208:209]
	v_lshl_add_u64 v[232:233], s[74:75], 0, v[232:233]
	v_pk_add_f32 v[126:127], v[126:127], v[238:239]
	v_pk_add_f32 v[124:125], v[124:125], v[236:237]
	v_lshl_add_u64 v[236:237], v[232:233], 0, v[206:207]
	v_pk_add_f32 v[122:123], v[122:123], v[234:235]
	global_store_dwordx4 v[236:237], v[124:127], off
	global_store_dwordx4 v[236:237], v[120:123], off offset:16
	v_cvt_pk_bf16_f32 v232, v124, v125
	v_cvt_pk_bf16_f32 v233, v126, v127
	v_cvt_pk_bf16_f32 v234, v120, v121
	v_pk_add_f32 v[118:119], v[118:119], v[182:183]
	v_mul_f32_e32 v125, v125, v125
	v_mul_f32_e32 v121, v121, v121
	v_fmac_f32_e32 v125, v124, v124
	v_mul_f32_e32 v124, v127, v127
	v_fmac_f32_e32 v121, v120, v120
	v_mul_f32_e32 v120, v123, v123
	v_fmac_f32_e32 v124, v126, v126
	v_fmac_f32_e32 v120, v122, v122
	v_add_f32_e32 v124, v125, v124
	v_add_f32_e32 v120, v121, v120
	v_pk_add_f32 v[116:117], v[116:117], v[180:181]
	v_pk_add_f32 v[112:113], v[112:113], v[176:177]
	v_cvt_pk_bf16_f32 v235, v122, v123
	global_store_dwordx4 v[224:225], v[232:235], off
	v_add_f32_e32 v124, v124, v120
	v_pk_add_f32 v[114:115], v[114:115], v[178:179]
	global_store_dwordx4 v[236:237], v[116:119], off offset:512
	global_store_dwordx4 v[236:237], v[112:115], off offset:528
	v_cvt_pk_bf16_f32 v120, v116, v117
	v_cvt_pk_bf16_f32 v121, v118, v119
	v_cvt_pk_bf16_f32 v122, v112, v113
	v_cvt_pk_bf16_f32 v123, v114, v115
	s_nop 0
	v_mul_f32_e32 v117, v117, v117
	v_mul_f32_e32 v113, v113, v113
	v_fmac_f32_e32 v113, v112, v112
	v_mul_f32_e32 v112, v115, v115
	v_fmac_f32_e32 v117, v116, v116
	v_mul_f32_e32 v116, v119, v119
	v_fmac_f32_e32 v112, v114, v114
	v_and_b32_e32 v114, 64, v222
	v_fmac_f32_e32 v116, v118, v118
	v_add_f32_e32 v112, v113, v112
	v_xor_b32_e32 v113, 16, v222
	v_add_u32_e32 v114, 64, v114
	v_add_f32_e32 v116, v117, v116
	v_cmp_lt_i32_e64 s[0:1], v113, v114
	v_add_f32_e32 v112, v116, v112
	v_add_f32_e32 v112, v124, v112
	v_cndmask_b32_e64 v113, v222, v113, s[0:1]
	v_lshlrev_b32_e32 v176, 2, v113
	ds_bpermute_b32 v113, v176, v112
	global_store_dwordx4 v[224:225], v[120:123], off offset:256
	s_waitcnt lgkmcnt(0)
	v_add_f32_e32 v112, v112, v113
	v_xor_b32_e32 v113, 32, v222
	v_cmp_lt_i32_e64 s[0:1], v113, v114
	s_nop 1
	v_cndmask_b32_e64 v113, v222, v113, s[0:1]
	v_lshlrev_b32_e32 v177, 2, v113
	ds_bpermute_b32 v113, v177, v112
	s_and_saveexec_b64 s[0:1], s[36:37]
	s_cbranch_execz .LBB0_466
	v_lshlrev_b64 v[114:115], 6, v[208:209]
	v_lshl_add_u64 v[114:115], s[22:23], 0, v[114:115]
	s_waitcnt lgkmcnt(0)
	v_add_f32_e32 v112, v112, v113
	global_store_dword v[114:115], v112, off

; __global__ void __launch_bounds__(NWAVES * 64, 2) hymba_fwd(Args args) {
;     ...
;                 pg8::Gemm gm{(const pg8::bf16_t*)(ws + WS_ACT), (const pg8::bf16_t*)(ws + WS_WDN) + (size_t)l * D * DFF, MT, D, DFF};
;                 pg8::StaticOrder S; S.init(MP, D, G, (int)blockIdx.x);
;                 pg8::EpiRes E{args.out + O_YP, args.out + O_YS, args.out, ws};
;                 if (PHMASK & 64) pg8::gemm_phase<pg8::EpiRes, pg8::StaticOrder, true, true>(lds, gm, S, E);
;                 for (int st = (int)blockIdx.x; st < 256; st += G)
;                     small_gemm_res(lds, (const bf16*)(ws + WS_ACT), (const bf16*)(ws + WS_WDN) + (size_t)l * D * DFF, DFF, args.out + O_YS, args.out, (bf16*)(ws + WS_AB), (float*)(ws + WS_PS), (st & 7) * 4 + ((st >> 3) & 3), st >> 5, tid);
.LBB0_483:
	v_readlane_b32 s0, v254, 44
	v_readlane_b32 s2, v255, 17
	v_readlane_b32 s3, v255, 18
	s_add_u32 s0, s0, s2
	v_readlane_b32 s1, v254, 45
	s_addc_u32 s1, s1, s3
	s_add_u32 s2, s2, s28
	s_waitcnt vmcnt(0)
	s_addc_u32 s3, s3, s7
	v_readlane_b32 s4, v254, 46
	s_add_u32 s2, s4, s2
	v_readlane_b32 s4, v254, 47
	v_readlane_b32 s48, v255, 23
	s_addc_u32 s3, s4, s3
	v_readlane_b32 s7, v254, 25
	v_readlane_b32 s20, v251, 0
	s_movk_i32 s29, 0x5800
	s_mov_b64 s[30:31], 0x100
	v_readlane_b32 s49, v255, 24
	s_barrier
	s_branch .LBB0_493
.LBB0_493:
	s_mov_b64 s[10:11], 0
